# barrier index moved from s98 to LDS control word (keeps baseline SGPR count)
# baseline (speedup 1.0000x reference)
_Z8fwd_mega6Params:
	s_load_dwordx4 s[4:7], s[0:1], 0x100
	v_and_b32_e32 v137, 0x3ff, v0
	v_writelane_b32 v242, s2, 0
	s_waitcnt lgkmcnt(0)
	v_writelane_b32 v242, s4, 1
	s_nop 1
	v_writelane_b32 v242, s5, 2
	v_writelane_b32 v242, s6, 3
	v_writelane_b32 v242, s7, 4
	v_cmp_eq_u32_e64 s[4:5], 0, v137
	s_mov_b64 s[2:3], exec
	s_nop 0
	v_writelane_b32 v242, s4, 5
	s_nop 1
	v_writelane_b32 v242, s5, 6
	s_and_b64 s[4:5], s[2:3], s[4:5]
	s_mov_b64 exec, s[4:5]
	s_add_i32 s4, 0, 0x12008
	v_mov_b32_e32 v2, 0
	v_mov_b32_e32 v3, v2
	v_mov_b32_e32 v1, s4
	ds_write_b64 v1, v[2:3]
	v_mov_b32_e32 v2, 1
	ds_write_b32 v1, v2 offset:8
	s_or_b64 exec, exec, s[2:3]
	s_load_dwordx4 s[4:7], s[0:1], 0x100
	s_waitcnt lgkmcnt(0)
	s_barrier
	s_add_u32 s2, s6, 0x30f4100
	s_addc_u32 s3, s7, 0
	v_writelane_b32 v242, s2, 7
	s_nop 1
	v_writelane_b32 v242, s3, 8
	s_getreg_b32 s2, hwreg(HW_REG_XCC_ID, 0, 4)
	s_and_b32 s2, s2, 15
	v_writelane_b32 v242, s2, 9
	s_mov_b64 s[2:3], exec
	v_readlane_b32 s4, v242, 5
	v_readlane_b32 s5, v242, 6
	s_and_b64 s[4:5], s[2:3], s[4:5]
	s_mov_b64 exec, s[4:5]
	s_cbranch_execz .LBB0_5
	s_mov_b64 s[4:5], exec
	v_mbcnt_lo_u32_b32 v1, s4, 0
	v_mbcnt_hi_u32_b32 v1, s5, v1
	v_cmp_eq_u32_e32 vcc, 0, v1
	s_and_b64 s[6:7], exec, vcc
	s_mov_b64 exec, s[6:7]
	s_cbranch_execz .LBB0_5
	v_readlane_b32 s6, v242, 9
	s_bcnt1_i32_b64 s4, s[4:5]
	s_lshl_b32 s6, s6, 8
	v_mov_b32_e32 v2, s4
	v_readlane_b32 s4, v242, 7
	v_mov_b32_e32 v1, s6
	v_readlane_b32 s5, v242, 8
	s_nop 4
	global_atomic_add v1, v2, s[4:5] offset:1024

.Lrp00_done:
.LBB0_218:
	s_or_b64 exec, exec, s[0:1]
	s_waitcnt vmcnt(0)
	s_barrier
	s_mov_b64 s[0:1], exec
	v_readlane_b32 s2, v242, 5
	v_readlane_b32 s3, v242, 6
	s_and_b64 s[2:3], s[0:1], s[2:3]
	s_xor_b64 s[0:1], s[2:3], s[0:1]
	s_mov_b64 exec, s[2:3]
	s_cbranch_execz .LBB0_271
	s_waitcnt vmcnt(0) lgkmcnt(0)
	v_mov_b32_e32 v5, 0x12008
	ds_read_b64 v[0:1], v5
	ds_read_b32 v6, v5 offset:8
	v_readlane_b32 s2, v242, 7
	v_readlane_b32 s3, v242, 8
	v_readlane_b32 s4, v242, 9
	v_mov_b32_e32 v2, 0
	v_mov_b32_e32 v3, 1
	s_lshl_b32 s4, s4, 8
	s_add_i32 s4, s4, 0x1400
	s_add_u32 s6, s2, s4
	s_addc_u32 s7, s3, 0
	s_add_u32 s8, s2, 0x3400
	s_addc_u32 s9, s3, 0
	global_atomic_add v4, v2, v3, s[6:7] sc0
	s_waitcnt lgkmcnt(0)
	v_readfirstlane_b32 s11, v0
	v_readfirstlane_b32 s12, v1
	v_readfirstlane_b32 s10, v6
	s_add_i32 s10, s10, 1
	v_mov_b32_e32 v6, s10
	ds_write_b32 v5, v6 offset:8
	s_mul_i32 s13, s10, s11
	s_mul_i32 s12, s10, s12
	s_waitcnt vmcnt(0)
	v_readfirstlane_b32 s14, v4
	s_add_i32 s14, s14, 1
	s_cmp_lg_u32 s14, s13
	s_cbranch_scc1 .Lxb1_wait
	buffer_wbl2 sc1
	s_waitcnt vmcnt(0)
	global_atomic_add v2, v3, s[8:9]

.Lxb1_done:
	buffer_inv sc1
	s_waitcnt vmcnt(0) lgkmcnt(0)

.LBB0_782:
	s_waitcnt vmcnt(0)
	s_waitcnt vmcnt(63) expcnt(7) lgkmcnt(15)
	s_barrier
	s_mov_b64 s[0:1], exec
	v_readlane_b32 s2, v242, 5
	v_readlane_b32 s3, v242, 6
	v_readlane_b32 s94, v241, 27
	s_and_b64 s[2:3], s[0:1], s[2:3]
	v_readlane_b32 s66, v241, 13
	v_readlane_b32 s95, v241, 28
	s_mov_b64 exec, s[2:3]
	s_cbranch_execz .LBB0_834
	s_waitcnt vmcnt(0) lgkmcnt(0)
	v_mov_b32_e32 v5, 0x12008
	ds_read_b64 v[0:1], v5
	ds_read_b32 v6, v5 offset:8
	v_readlane_b32 s2, v242, 7
	v_readlane_b32 s3, v242, 8
	v_readlane_b32 s4, v242, 9
	v_mov_b32_e32 v2, 0
	v_mov_b32_e32 v3, 1
	s_lshl_b32 s4, s4, 8
	s_add_i32 s4, s4, 0x1400
	s_add_u32 s6, s2, s4
	s_addc_u32 s7, s3, 0
	s_add_u32 s8, s2, 0x3400
	s_addc_u32 s9, s3, 0
	global_atomic_add v4, v2, v3, s[6:7] sc0
	s_waitcnt lgkmcnt(0)
	v_readfirstlane_b32 s11, v0
	v_readfirstlane_b32 s12, v1
	v_readfirstlane_b32 s10, v6
	s_add_i32 s10, s10, 1
	v_mov_b32_e32 v6, s10
	ds_write_b32 v5, v6 offset:8
	s_mul_i32 s13, s10, s11
	s_mul_i32 s12, s10, s12
	s_waitcnt vmcnt(0)
	v_readfirstlane_b32 s14, v4
	s_add_i32 s14, s14, 1
	s_cmp_lg_u32 s14, s13
	s_cbranch_scc1 .Lxb2_wait
	buffer_wbl2 sc1
	s_waitcnt vmcnt(0)
	global_atomic_add v2, v3, s[8:9]

.LBB0_853:
	s_waitcnt vmcnt(0)
	s_barrier
	s_mov_b64 s[0:1], exec
	v_readlane_b32 s2, v242, 5
	v_readlane_b32 s3, v242, 6
	s_and_b64 s[2:3], s[0:1], s[2:3]
	s_mov_b64 exec, s[2:3]
	s_cbranch_execz .LBB0_905
	s_waitcnt vmcnt(0) lgkmcnt(0)
	v_mov_b32_e32 v5, 0x12008
	ds_read_b64 v[0:1], v5
	ds_read_b32 v6, v5 offset:8
	v_readlane_b32 s2, v242, 7
	v_readlane_b32 s3, v242, 8
	v_readlane_b32 s4, v242, 9
	v_mov_b32_e32 v2, 0
	v_mov_b32_e32 v3, 1
	s_lshl_b32 s4, s4, 8
	s_add_i32 s4, s4, 0x1400
	s_add_u32 s6, s2, s4
	s_addc_u32 s7, s3, 0
	s_add_u32 s8, s2, 0x3400
	s_addc_u32 s9, s3, 0
	global_atomic_add v4, v2, v3, s[6:7] sc0
	s_waitcnt lgkmcnt(0)
	v_readfirstlane_b32 s11, v0
	v_readfirstlane_b32 s12, v1
	v_readfirstlane_b32 s10, v6
	s_add_i32 s10, s10, 1
	v_mov_b32_e32 v6, s10
	ds_write_b32 v5, v6 offset:8
	s_mul_i32 s13, s10, s11
	s_mul_i32 s12, s10, s12
	s_waitcnt vmcnt(0)
	v_readfirstlane_b32 s14, v4
	s_add_i32 s14, s14, 1
	s_cmp_lg_u32 s14, s13
	s_cbranch_scc1 .Lxb3_wait
	buffer_wbl2 sc1
	s_waitcnt vmcnt(0)
	global_atomic_add v2, v3, s[8:9]

.LBB0_978:
	s_waitcnt vmcnt(0)
	s_barrier
	s_mov_b64 s[0:1], exec
	v_readlane_b32 s2, v242, 5
	v_readlane_b32 s3, v242, 6
	v_readlane_b32 s44, v242, 58
	v_readlane_b32 s72, v242, 54
	v_readlane_b32 s58, v242, 56
	s_and_b64 s[2:3], s[0:1], s[2:3]
	v_readlane_b32 s45, v242, 59
	v_readlane_b32 s73, v242, 55
	v_readlane_b32 s59, v242, 57
	s_mov_b64 exec, s[2:3]
	s_cbranch_execz .LBB0_1030
	s_waitcnt vmcnt(0) lgkmcnt(0)
	v_mov_b32_e32 v5, 0x12008
	ds_read_b64 v[0:1], v5
	ds_read_b32 v6, v5 offset:8
	v_readlane_b32 s2, v242, 7
	v_readlane_b32 s3, v242, 8
	v_readlane_b32 s4, v242, 9
	v_mov_b32_e32 v2, 0
	v_mov_b32_e32 v3, 1
	s_lshl_b32 s4, s4, 8
	s_add_i32 s4, s4, 0x1400
	s_add_u32 s6, s2, s4
	s_addc_u32 s7, s3, 0
	s_add_u32 s8, s2, 0x3400
	s_addc_u32 s9, s3, 0
	global_atomic_add v4, v2, v3, s[6:7] sc0
	s_waitcnt lgkmcnt(0)
	v_readfirstlane_b32 s11, v0
	v_readfirstlane_b32 s12, v1
	v_readfirstlane_b32 s10, v6
	s_add_i32 s10, s10, 1
	v_mov_b32_e32 v6, s10
	ds_write_b32 v5, v6 offset:8
	s_mul_i32 s13, s10, s11
	s_mul_i32 s12, s10, s12
	s_waitcnt vmcnt(0)
	v_readfirstlane_b32 s14, v4
	s_add_i32 s14, s14, 1
	s_cmp_lg_u32 s14, s13
	s_cbranch_scc1 .Lxb4_wait
	buffer_wbl2 sc1
	s_waitcnt vmcnt(0)
	global_atomic_add v2, v3, s[8:9]

.Lpo0_done:
.LBB0_1033:
	s_or_b64 exec, exec, s[0:1]
	s_waitcnt vmcnt(0)
	s_barrier
	s_mov_b64 s[0:1], exec
	v_readlane_b32 s2, v242, 5
	v_readlane_b32 s3, v242, 6
	s_and_b64 s[2:3], s[0:1], s[2:3]
	v_readlane_b32 s41, v241, 14
	s_mov_b64 exec, s[2:3]
	s_cbranch_execz .LBB0_1085
	s_waitcnt vmcnt(0) lgkmcnt(0)
	v_mov_b32_e32 v5, 0x12008
	ds_read_b64 v[0:1], v5
	ds_read_b32 v6, v5 offset:8
	v_readlane_b32 s2, v242, 7
	v_readlane_b32 s3, v242, 8
	v_readlane_b32 s4, v242, 9
	v_mov_b32_e32 v2, 0
	v_mov_b32_e32 v3, 1
	s_lshl_b32 s4, s4, 8
	s_add_i32 s4, s4, 0x1400
	s_add_u32 s6, s2, s4
	s_addc_u32 s7, s3, 0
	s_add_u32 s8, s2, 0x3400
	s_addc_u32 s9, s3, 0
	global_atomic_add v4, v2, v3, s[6:7] sc0
	s_waitcnt lgkmcnt(0)
	v_readfirstlane_b32 s11, v0
	v_readfirstlane_b32 s12, v1
	v_readfirstlane_b32 s10, v6
	s_add_i32 s10, s10, 1
	v_mov_b32_e32 v6, s10
	ds_write_b32 v5, v6 offset:8
	s_mul_i32 s13, s10, s11
	s_mul_i32 s12, s10, s12
	s_waitcnt vmcnt(0)
	v_readfirstlane_b32 s14, v4
	s_add_i32 s14, s14, 1
	s_cmp_lg_u32 s14, s13
	s_cbranch_scc1 .Lxb5_wait
	buffer_wbl2 sc1
	s_waitcnt vmcnt(0)
	global_atomic_add v2, v3, s[8:9]

.LBB0_1091:
	s_waitcnt vmcnt(0)
	s_waitcnt vmcnt(63) expcnt(7) lgkmcnt(15)
	s_barrier
	s_mov_b64 s[0:1], exec
	v_readlane_b32 s2, v242, 5
	v_readlane_b32 s3, v242, 6
	s_and_b64 s[2:3], s[0:1], s[2:3]
	s_mov_b64 exec, s[2:3]
	s_cbranch_execz .LBB0_1143
	s_waitcnt vmcnt(0) lgkmcnt(0)
	v_mov_b32_e32 v5, 0x12008
	ds_read_b64 v[0:1], v5
	ds_read_b32 v6, v5 offset:8
	v_readlane_b32 s2, v242, 7
	v_readlane_b32 s3, v242, 8
	v_readlane_b32 s4, v242, 9
	v_mov_b32_e32 v2, 0
	v_mov_b32_e32 v3, 1
	s_lshl_b32 s4, s4, 8
	s_add_i32 s4, s4, 0x1400
	s_add_u32 s6, s2, s4
	s_addc_u32 s7, s3, 0
	s_add_u32 s8, s2, 0x3400
	s_addc_u32 s9, s3, 0
	global_atomic_add v4, v2, v3, s[6:7] sc0
	s_waitcnt lgkmcnt(0)
	v_readfirstlane_b32 s11, v0
	v_readfirstlane_b32 s12, v1
	v_readfirstlane_b32 s10, v6
	s_add_i32 s10, s10, 1
	v_mov_b32_e32 v6, s10
	ds_write_b32 v5, v6 offset:8
	s_mul_i32 s13, s10, s11
	s_mul_i32 s12, s10, s12
	s_waitcnt vmcnt(0)
	v_readfirstlane_b32 s14, v4
	s_add_i32 s14, s14, 1
	s_cmp_lg_u32 s14, s13
	s_cbranch_scc1 .Lxb6_wait
	buffer_wbl2 sc1
	s_waitcnt vmcnt(0)
	global_atomic_add v2, v3, s[8:9]

.LBB0_1149:
	s_or_b64 exec, exec, s[2:3]
	s_waitcnt vmcnt(0)
	s_barrier
	s_mov_b64 s[0:1], exec
	v_readlane_b32 s2, v242, 5
	v_readlane_b32 s3, v242, 6
	s_and_b64 s[2:3], s[0:1], s[2:3]
	s_mov_b64 exec, s[2:3]
	s_cbranch_execz .LBB0_1201
	s_waitcnt vmcnt(0) lgkmcnt(0)
	v_mov_b32_e32 v5, 0x12008
	ds_read_b64 v[0:1], v5
	ds_read_b32 v6, v5 offset:8
	v_readlane_b32 s2, v242, 7
	v_readlane_b32 s3, v242, 8
	v_readlane_b32 s4, v242, 9
	v_mov_b32_e32 v2, 0
	v_mov_b32_e32 v3, 1
	s_lshl_b32 s4, s4, 8
	s_add_i32 s4, s4, 0x1400
	s_add_u32 s6, s2, s4
	s_addc_u32 s7, s3, 0
	s_add_u32 s8, s2, 0x3400
	s_addc_u32 s9, s3, 0
	global_atomic_add v4, v2, v3, s[6:7] sc0
	s_waitcnt lgkmcnt(0)
	v_readfirstlane_b32 s11, v0
	v_readfirstlane_b32 s12, v1
	v_readfirstlane_b32 s10, v6
	s_add_i32 s10, s10, 1
	v_mov_b32_e32 v6, s10
	ds_write_b32 v5, v6 offset:8
	s_mul_i32 s13, s10, s11
	s_mul_i32 s12, s10, s12
	s_waitcnt vmcnt(0)
	v_readfirstlane_b32 s14, v4
	s_add_i32 s14, s14, 1
	s_cmp_lg_u32 s14, s13
	s_cbranch_scc1 .Lxb7_wait
	buffer_wbl2 sc1
	s_waitcnt vmcnt(0)
	global_atomic_add v2, v3, s[8:9]

.LBB0_1207:
	s_waitcnt vmcnt(0)
	s_barrier
	s_mov_b64 s[0:1], exec
	v_readlane_b32 s2, v242, 5
	v_readlane_b32 s3, v242, 6
	v_readlane_b32 s46, v242, 52
	s_and_b64 s[2:3], s[0:1], s[2:3]
	v_readlane_b32 s47, v242, 53
	s_mov_b64 exec, s[2:3]
	s_cbranch_execz .LBB0_1259
	s_waitcnt vmcnt(0) lgkmcnt(0)
	v_mov_b32_e32 v5, 0x12008
	ds_read_b64 v[0:1], v5
	ds_read_b32 v6, v5 offset:8
	v_readlane_b32 s2, v242, 7
	v_readlane_b32 s3, v242, 8
	v_readlane_b32 s4, v242, 9
	v_mov_b32_e32 v2, 0
	v_mov_b32_e32 v3, 1
	s_lshl_b32 s4, s4, 8
	s_add_i32 s4, s4, 0x1400
	s_add_u32 s6, s2, s4
	s_addc_u32 s7, s3, 0
	s_add_u32 s8, s2, 0x3400
	s_addc_u32 s9, s3, 0
	global_atomic_add v4, v2, v3, s[6:7] sc0
	s_waitcnt lgkmcnt(0)
	v_readfirstlane_b32 s11, v0
	v_readfirstlane_b32 s12, v1
	v_readfirstlane_b32 s10, v6
	s_add_i32 s10, s10, 1
	v_mov_b32_e32 v6, s10
	ds_write_b32 v5, v6 offset:8
	s_mul_i32 s13, s10, s11
	s_mul_i32 s12, s10, s12
	s_waitcnt vmcnt(0)
	v_readfirstlane_b32 s14, v4
	s_add_i32 s14, s14, 1
	s_cmp_lg_u32 s14, s13
	s_cbranch_scc1 .Lxb8_wait
	buffer_wbl2 sc1
	s_waitcnt vmcnt(0)
	global_atomic_add v2, v3, s[8:9]

.Lrp20_done:
.LBB0_1322:
	s_or_b64 exec, exec, s[0:1]
	s_waitcnt vmcnt(0)
	s_barrier
	s_mov_b64 s[0:1], exec
	v_readlane_b32 s2, v242, 5
	v_readlane_b32 s3, v242, 6
	s_and_b64 s[2:3], s[0:1], s[2:3]
	s_mov_b64 exec, s[2:3]
	s_cbranch_execz .LBB0_1374
	s_waitcnt vmcnt(0) lgkmcnt(0)
	v_mov_b32_e32 v5, 0x12008
	ds_read_b64 v[0:1], v5
	ds_read_b32 v6, v5 offset:8
	v_readlane_b32 s2, v242, 7
	v_readlane_b32 s3, v242, 8
	v_readlane_b32 s4, v242, 9
	v_mov_b32_e32 v2, 0
	v_mov_b32_e32 v3, 1
	s_lshl_b32 s4, s4, 8
	s_add_i32 s4, s4, 0x1400
	s_add_u32 s6, s2, s4
	s_addc_u32 s7, s3, 0
	s_add_u32 s8, s2, 0x3400
	s_addc_u32 s9, s3, 0
	global_atomic_add v4, v2, v3, s[6:7] sc0
	s_waitcnt lgkmcnt(0)
	v_readfirstlane_b32 s11, v0
	v_readfirstlane_b32 s12, v1
	v_readfirstlane_b32 s10, v6
	s_add_i32 s10, s10, 1
	v_mov_b32_e32 v6, s10
	ds_write_b32 v5, v6 offset:8
	s_mul_i32 s13, s10, s11
	s_mul_i32 s12, s10, s12
	s_waitcnt vmcnt(0)
	v_readfirstlane_b32 s14, v4
	s_add_i32 s14, s14, 1
	s_cmp_lg_u32 s14, s13
	s_cbranch_scc1 .Lxb10_wait
	buffer_wbl2 sc1
	s_waitcnt vmcnt(0)
	global_atomic_add v2, v3, s[8:9]

.LBB0_1779:
	s_waitcnt vmcnt(0)
	s_waitcnt vmcnt(63) expcnt(7) lgkmcnt(15)
	s_barrier
	s_mov_b64 s[0:1], exec
	v_readlane_b32 s2, v242, 5
	v_readlane_b32 s3, v242, 6
	v_readlane_b32 s76, v241, 16
	v_readlane_b32 s80, v241, 18
	s_and_b64 s[2:3], s[0:1], s[2:3]
	v_readlane_b32 s77, v241, 17
	v_readlane_b32 s78, v241, 15
	v_readlane_b32 s79, v241, 20
	v_readlane_b32 s81, v241, 19
	s_mov_b64 exec, s[2:3]
	s_cbranch_execz .LBB0_1831
	s_waitcnt vmcnt(0) lgkmcnt(0)
	v_mov_b32_e32 v5, 0x12008
	ds_read_b64 v[0:1], v5
	ds_read_b32 v6, v5 offset:8
	v_readlane_b32 s2, v242, 7
	v_readlane_b32 s3, v242, 8
	v_readlane_b32 s4, v242, 9
	v_mov_b32_e32 v2, 0
	v_mov_b32_e32 v3, 1
	s_lshl_b32 s4, s4, 8
	s_add_i32 s4, s4, 0x1400
	s_add_u32 s6, s2, s4
	s_addc_u32 s7, s3, 0
	s_add_u32 s8, s2, 0x3400
	s_addc_u32 s9, s3, 0
	global_atomic_add v4, v2, v3, s[6:7] sc0
	s_waitcnt lgkmcnt(0)
	v_readfirstlane_b32 s11, v0
	v_readfirstlane_b32 s12, v1
	v_readfirstlane_b32 s10, v6
	s_add_i32 s10, s10, 1
	v_mov_b32_e32 v6, s10
	ds_write_b32 v5, v6 offset:8
	s_mul_i32 s13, s10, s11
	s_mul_i32 s12, s10, s12
	s_waitcnt vmcnt(0)
	v_readfirstlane_b32 s14, v4
	s_add_i32 s14, s14, 1
	s_cmp_lg_u32 s14, s13
	s_cbranch_scc1 .Lxb11_wait
	buffer_wbl2 sc1
	s_waitcnt vmcnt(0)
	global_atomic_add v2, v3, s[8:9]

.Lpo1_done:
.LBB0_2031:
	s_or_b64 exec, exec, s[0:1]
	s_waitcnt vmcnt(0)
	s_barrier
	s_mov_b64 s[0:1], exec
	v_readlane_b32 s2, v242, 5
	v_readlane_b32 s3, v242, 6
	v_readlane_b32 s44, v241, 45
	s_and_b64 s[2:3], s[0:1], s[2:3]
	v_readlane_b32 s45, v241, 46
	v_readlane_b32 s56, v242, 56
	v_readlane_b32 s57, v242, 54
	s_mov_b64 exec, s[2:3]
	s_cbranch_execz .LBB0_2083
	s_waitcnt vmcnt(0) lgkmcnt(0)
	v_mov_b32_e32 v5, 0x12008
	ds_read_b64 v[0:1], v5
	ds_read_b32 v6, v5 offset:8
	v_readlane_b32 s2, v242, 7
	v_readlane_b32 s3, v242, 8
	v_readlane_b32 s4, v242, 9
	v_mov_b32_e32 v2, 0
	v_mov_b32_e32 v3, 1
	s_lshl_b32 s4, s4, 8
	s_add_i32 s4, s4, 0x1400
	s_add_u32 s6, s2, s4
	s_addc_u32 s7, s3, 0
	s_add_u32 s8, s2, 0x3400
	s_addc_u32 s9, s3, 0
	global_atomic_add v4, v2, v3, s[6:7] sc0
	s_waitcnt lgkmcnt(0)
	v_readfirstlane_b32 s11, v0
	v_readfirstlane_b32 s12, v1
	v_readfirstlane_b32 s10, v6
	s_add_i32 s10, s10, 1
	v_mov_b32_e32 v6, s10
	ds_write_b32 v5, v6 offset:8
	s_mul_i32 s13, s10, s11
	s_mul_i32 s12, s10, s12
	s_waitcnt vmcnt(0)
	v_readfirstlane_b32 s14, v4
	s_add_i32 s14, s14, 1
	s_cmp_lg_u32 s14, s13
	s_cbranch_scc1 .Lxb14_wait
	buffer_wbl2 sc1
	s_waitcnt vmcnt(0)
	global_atomic_add v2, v3, s[8:9]

.LBB0_2147:
	s_or_b64 exec, exec, s[0:1]
	s_waitcnt vmcnt(0)
	s_barrier
	s_mov_b64 s[0:1], exec
	v_readlane_b32 s2, v242, 5
	v_readlane_b32 s3, v242, 6
	s_and_b64 s[2:3], s[0:1], s[2:3]
	s_mov_b64 exec, s[2:3]
	s_cbranch_execz .LBB0_2199
	s_waitcnt vmcnt(0) lgkmcnt(0)
	v_mov_b32_e32 v5, 0x12008
	ds_read_b64 v[0:1], v5
	ds_read_b32 v6, v5 offset:8
	v_readlane_b32 s2, v242, 7
	v_readlane_b32 s3, v242, 8
	v_readlane_b32 s4, v242, 9
	v_mov_b32_e32 v2, 0
	v_mov_b32_e32 v3, 1
	s_lshl_b32 s4, s4, 8
	s_add_i32 s4, s4, 0x1400
	s_add_u32 s6, s2, s4
	s_addc_u32 s7, s3, 0
	s_add_u32 s8, s2, 0x3400
	s_addc_u32 s9, s3, 0
	global_atomic_add v4, v2, v3, s[6:7] sc0
	s_waitcnt lgkmcnt(0)
	v_readfirstlane_b32 s11, v0
	v_readfirstlane_b32 s12, v1
	v_readfirstlane_b32 s10, v6
	s_add_i32 s10, s10, 1
	v_mov_b32_e32 v6, s10
	ds_write_b32 v5, v6 offset:8
	s_mul_i32 s13, s10, s11
	s_mul_i32 s12, s10, s12
	s_waitcnt vmcnt(0)
	v_readfirstlane_b32 s14, v4
	s_add_i32 s14, s14, 1
	s_cmp_lg_u32 s14, s13
	s_cbranch_scc1 .Lxb16_wait
	buffer_wbl2 sc1
	s_waitcnt vmcnt(0)
	global_atomic_add v2, v3, s[8:9]

.LBB0_2205:
	s_waitcnt vmcnt(0)
	s_barrier
	s_mov_b64 s[0:1], exec
	v_readlane_b32 s2, v242, 5
	v_readlane_b32 s3, v242, 6
	v_readlane_b32 s36, v241, 29
	s_and_b64 s[2:3], s[0:1], s[2:3]
	v_readlane_b32 s48, v241, 41
	v_readlane_b32 s49, v241, 42
	v_readlane_b32 s37, v241, 30
	v_readlane_b32 s38, v241, 31
	v_readlane_b32 s39, v241, 32
	v_readlane_b32 s40, v241, 33
	v_readlane_b32 s41, v241, 34
	v_readlane_b32 s42, v241, 35
	v_readlane_b32 s43, v241, 36
	v_readlane_b32 s44, v241, 37
	v_readlane_b32 s45, v241, 38
	v_readlane_b32 s46, v241, 39
	v_readlane_b32 s47, v241, 40
	v_readlane_b32 s50, v241, 43
	v_readlane_b32 s51, v241, 44
	s_mov_b64 exec, s[2:3]
	s_cbranch_execz .LBB0_2257
	s_waitcnt vmcnt(0) lgkmcnt(0)
	v_mov_b32_e32 v5, 0x12008
	ds_read_b64 v[0:1], v5
	ds_read_b32 v6, v5 offset:8
	v_readlane_b32 s2, v242, 7
	v_readlane_b32 s3, v242, 8
	v_readlane_b32 s4, v242, 9
	v_mov_b32_e32 v2, 0
	v_mov_b32_e32 v3, 1
	s_lshl_b32 s4, s4, 8
	s_add_i32 s4, s4, 0x1400
	s_add_u32 s6, s2, s4
	s_addc_u32 s7, s3, 0
	s_add_u32 s8, s2, 0x3400
	s_addc_u32 s9, s3, 0
	global_atomic_add v4, v2, v3, s[6:7] sc0
	s_waitcnt lgkmcnt(0)
	v_readfirstlane_b32 s11, v0
	v_readfirstlane_b32 s12, v1
	v_readfirstlane_b32 s10, v6
	s_add_i32 s10, s10, 1
	v_mov_b32_e32 v6, s10
	ds_write_b32 v5, v6 offset:8
	s_mul_i32 s13, s10, s11
	s_mul_i32 s12, s10, s12
	s_waitcnt vmcnt(0)
	v_readfirstlane_b32 s14, v4
	s_add_i32 s14, s14, 1
	s_cmp_lg_u32 s14, s13
	s_cbranch_scc1 .Lxb17_wait
	buffer_wbl2 sc1
	s_waitcnt vmcnt(0)
	global_atomic_add v2, v3, s[8:9]
